# drop buffer_wbl2 at barriers after P3,P4,P5 (write-through-only phases); SSQ store sc1
# baseline (speedup 1.0000x reference)
.LBB0_467:
	s_andn2_saveexec_b64 s[8:9], s[8:9]
	s_cbranch_execz .LBB0_487
	s_mov_b64 s[8:9], exec
	s_waitcnt lgkmcnt(0)
	s_waitcnt vmcnt(0)
	v_mbcnt_lo_u32_b32 v1, s8, 0
	v_mbcnt_hi_u32_b32 v1, s9, v1
	v_cmp_eq_u32_e32 vcc, 0, v1
	s_and_saveexec_b64 s[10:11], vcc
	s_cbranch_execz .LBB0_470
	s_bcnt1_i32_b64 s8, s[8:9]
	v_mov_b32_e32 v2, 0x2383000
	v_mov_b32_e32 v3, s8
	global_atomic_add v2, v2, v3, s[80:81] offset:1024 sc0

.LBB0_523:
	s_or_b64 exec, exec, s[38:39]
	s_waitcnt lgkmcnt(0)
	s_barrier
	s_and_saveexec_b64 s[38:39], s[4:5]
	s_cbranch_execz .LBB0_525
	v_add_u32_e32 v0, 0, v196
	v_add_u32_e32 v0, 0x20000, v0
	s_waitcnt lgkmcnt(0)
	ds_read_b128 v[0:3], v0
	v_or_b32_e32 v4, s19, v216
	v_ashrrev_i32_e32 v5, 31, v4
	s_ashr_i32 s19, s18, 31
	s_waitcnt lgkmcnt(0)
	v_mov_b32_e32 v6, v1
	v_mov_b32_e32 v7, v2
	v_mov_b32_e32 v1, v3
	v_pk_add_f32 v[0:1], v[6:7], v[0:1]
	s_nop 0
	v_add_f32_e32 v2, v0, v1
	v_lshl_add_u64 v[0:1], v[4:5], 4, s[14:15]
	v_lshl_add_u64 v[0:1], s[18:19], 2, v[0:1]
	global_store_dword v[0:1], v2, off sc1
